# attention: next row's V-piece LDS-DMA issued right after the PV barrier (B5) instead of after the merge barrier, and the top-of-step wait counts exactly what may stay in flight (V piece + this wave's
# baseline (speedup 1.0000x reference)
; #define LAS __attribute__((address_space(3)))
; #define MFMA16(a, b, c) __builtin_amdgcn_mfma_f32_16x16x32_bf16((a), (b), (c), 0, 0, 0)
; #define SCHED_FENCE() __builtin_amdgcn_sched_barrier(0)
; __device__ __forceinline__ int att_fk(int key) { return ((key >> 3) & 3) + 4 * ((key >> 1) & 1); }
; #define ATT_K_PIECE(h_, row_, kg_) do { const int key = (kg_) * 8 + lr; \
;         __builtin_amdgcn_global_load_lds((const __attribute__((address_space(1))) unsigned*)(Kb + ((size_t)(row_) * 64 + key) * 1024 + (h_) * 64 + 8 * (lc ^ att_fk(key))), (LAS unsigned*)(KL + ((row_) & 7) * 8192 + (kg_) * 1024), 16, 0, 0); } while (0)
; __device__ __forceinline__ void attn_phase(const bf16_t* Q, const bf16_t* Kb, const bf16_t* VTa, const float* rpb, bf16_t* Y, LAS unsigned char* lds, int bx, int G, int tid, int wave, int lane) {
;     ...
;         for (int n = 0; n < 8; ++n) {
;             const int r = r0 + n, rs = min(max(r - 4, 0), 120);
;             const bool has_next = n < 7; const int rsn = min(max(r + 1 - 4, 0), 120); const bool newrow = has_next && (rsn != rs);
;             asm volatile("s_waitcnt vmcnt(1)" ::: "memory");
;             ATT_BAR();
;             f32x4 s[4][2];
;             float mx = -3.0e38f;
; #pragma unroll
;             for (int ii = 0; ii < 4; ++ii) {
;                 const int i = 4 * hf + ii, dr = rs + i - r + 7;
;                 float bia[8];
; #pragma unroll
;                 for (int j = 0; j < 8; ++j) bia[j] = rl[((unsigned)(j - wlo) < (unsigned)wwd) ? dr * 31 + dci0 + j : 480];
; #pragma unroll
;                 for (int ta = 0; ta < 2; ++ta) {
;                     const int key = cs + 8 * (fr >> 2) + 4 * ta + (fr & 3), fk = att_fk(key);
;                     const LAS unsigned char* kp = KL + ((rs + i) & 7) * 8192 + key * 128;
;                     const bf16x8 kf0 = *(const LAS bf16x8*)(kp + ((fq ^ fk) << 4)), kf1 = *(const LAS bf16x8*)(kp + (((4 + fq) ^ fk) << 4));
;                     f32x4 a = {0.f, 0.f, 0.f, 0.f};
;                     a = MFMA16(kf0, qf0, a); a = MFMA16(kf1, qf1, a);
; #pragma unroll
;                     for (int idx = 0; idx < 4; ++idx) { a[idx] += bia[4 * ta + idx]; mx = fmaxf(mx, a[idx]); }
;                     s[ii][ta] = a;
;                 }
;             }
;             ATT_BAR();
;             SCHED_FENCE();
;             if (newrow) ATT_K_PIECE(h, rs + 8, wave);
.LBB0_451:
	s_max_i32 s31, s94, 4
	s_add_i32 s31, s31, -4
	s_max_i32 s56, s94, 3
	s_min_u32 s64, s31, 0x78
	s_add_i32 s56, s56, -3
	s_add_i32 s58, s95, s64
	s_add_i32 s59, s20, s64
	s_min_u32 s80, s56, 0x78
	s_cmp_lg_u32 s80, s64
	s_cselect_b64 s[56:57], -1, 0
	s_add_i32 s59, s30, s59
	s_add_i32 s60, s64, s85
	s_mul_i32 s61, s59, 31
	s_add_i32 s74, s61, 0xffffff27
	s_lshl_b32 s59, s60, 13
	s_and_b32 s75, s59, 0xe000
	v_add_u32_e32 v10, s74, v46
	s_and_b32 s26, s12, 2
	s_add_i32 s26, s26, s32
	s_cmp_lg_u32 s26, 0
	s_cbranch_scc1 .Ltop1_a
	s_waitcnt vmcnt(0)
	s_branch .Ltop1_d
.Ltop1_a:
	s_cmp_lg_u32 s26, 1
	s_cbranch_scc1 .Ltop1_b
	s_waitcnt vmcnt(1)
	s_branch .Ltop1_d
.Ltop1_b:
	s_cmp_lg_u32 s26, 2
	s_cbranch_scc1 .Ltop1_c
	s_waitcnt vmcnt(2)
	s_branch .Ltop1_d
.Ltop1_c:
	s_waitcnt vmcnt(3)
.Ltop1_d:
	v_lshl_add_u32 v190, v10, 2, s84
	v_cndmask_b32_e64 v11, v194, v190, s[40:41]
	v_add_u32_e32 v14, s75, v61
	s_waitcnt lgkmcnt(0)
	s_barrier
	v_add_u32_e32 v19, v14, v55
	ds_read_b32 v202, v11
	v_add_u32_e32 v18, v14, v41
	ds_read_b128 v[14:17], v19
	v_cndmask_b32_e64 v11, v195, v190, s[42:43]
	ds_read_b32 v203, v11 offset:4
	v_cndmask_b32_e64 v11, v196, v190, s[44:45]
	ds_read_b32 v204, v11 offset:8
	v_cndmask_b32_e64 v11, v197, v190, s[46:47]
	ds_read_b32 v205, v11 offset:12
	v_cndmask_b32_e64 v11, v198, v190, s[48:49]
	ds_read_b32 v206, v11 offset:16
	v_cndmask_b32_e64 v11, v199, v190, s[50:51]
	ds_read_b32 v207, v11 offset:20
	v_cndmask_b32_e64 v11, v200, v190, s[52:53]
	v_cndmask_b32_e64 v10, v201, v190, s[54:55]
	ds_read_b32 v208, v11 offset:24
	ds_read_b32 v209, v10 offset:28
	ds_read_b128 v[10:13], v18
	s_waitcnt lgkmcnt(0)
	v_mfma_f32_16x16x32_bf16 v[10:13], v[10:13], v[6:9], 0
	s_add_i32 s59, s64, s89
	s_add_i32 vcc_hi, s61, 0xffffff46
	s_lshl_b32 s59, s59, 13
	v_mfma_f32_16x16x32_bf16 v[10:13], v[14:17], v[2:5], v[10:13]
	ds_read_b128 v[14:17], v18 offset:512
	ds_read_b128 v[18:21], v19 offset:512
	s_and_b32 vcc_lo, s59, 0xe000
	v_add_u32_e32 v22, vcc_lo, v61
	s_waitcnt lgkmcnt(1)
	v_mfma_f32_16x16x32_bf16 v[14:17], v[14:17], v[6:9], 0
	v_add_u32_e32 v27, v22, v55
	v_add_u32_e32 v26, v22, v41
	ds_read_b128 v[22:25], v27
	s_waitcnt lgkmcnt(1)
	v_mfma_f32_16x16x32_bf16 v[14:17], v[18:21], v[2:5], v[14:17]
	v_add_u32_e32 v18, vcc_hi, v46
	v_lshl_add_u32 v191, v18, 2, s84
	v_cndmask_b32_e64 v19, v194, v191, s[40:41]
	ds_read_b32 v210, v19
	v_cndmask_b32_e64 v19, v195, v191, s[42:43]
	ds_read_b32 v211, v19 offset:4
	v_cndmask_b32_e64 v19, v196, v191, s[44:45]
	ds_read_b32 v212, v19 offset:8
	v_cndmask_b32_e64 v19, v197, v191, s[46:47]
	ds_read_b32 v213, v19 offset:12
	v_cndmask_b32_e64 v19, v198, v191, s[48:49]
	ds_read_b32 v214, v19 offset:16
	v_cndmask_b32_e64 v19, v199, v191, s[50:51]
	ds_read_b32 v215, v19 offset:20
	v_cndmask_b32_e64 v19, v200, v191, s[52:53]
	v_cndmask_b32_e64 v18, v201, v191, s[54:55]
	ds_read_b32 v216, v19 offset:24
	ds_read_b32 v217, v18 offset:28
	ds_read_b128 v[18:21], v26
	s_waitcnt lgkmcnt(0)
	v_mfma_f32_16x16x32_bf16 v[18:21], v[18:21], v[6:9], 0
	s_add_i32 s59, s64, s90
	s_addk_i32 s61, 0xff65
	s_lshl_b32 s59, s59, 13
	v_mfma_f32_16x16x32_bf16 v[18:21], v[22:25], v[2:5], v[18:21]
	ds_read_b128 v[22:25], v26 offset:512
	ds_read_b128 v[26:29], v27 offset:512
	s_and_b32 s60, s59, 0xe000
	v_add_u32_e32 v30, s60, v61
	s_waitcnt lgkmcnt(1)
	v_mfma_f32_16x16x32_bf16 v[22:25], v[22:25], v[6:9], 0
	v_add_u32_e32 v35, v30, v55
	v_add_u32_e32 v34, v30, v41
	ds_read_b128 v[30:33], v35
	s_waitcnt lgkmcnt(1)
	v_mfma_f32_16x16x32_bf16 v[22:25], v[26:29], v[2:5], v[22:25]
	v_add_u32_e32 v26, s61, v46
	v_lshl_add_u32 v192, v26, 2, s84
	v_cndmask_b32_e64 v27, v194, v192, s[40:41]
	ds_read_b32 v102, v27
	v_cndmask_b32_e64 v27, v195, v192, s[42:43]
	ds_read_b32 v103, v27 offset:4
	v_cndmask_b32_e64 v27, v196, v192, s[44:45]
	ds_read_b32 v104, v27 offset:8
	v_cndmask_b32_e64 v27, v197, v192, s[46:47]
	ds_read_b32 v105, v27 offset:12
	v_cndmask_b32_e64 v27, v198, v192, s[48:49]
	ds_read_b32 v106, v27 offset:16
	v_cndmask_b32_e64 v27, v199, v192, s[50:51]
	ds_read_b32 v107, v27 offset:20
	v_cndmask_b32_e64 v27, v200, v192, s[52:53]
	v_cndmask_b32_e64 v26, v201, v192, s[54:55]
	ds_read_b32 v108, v27 offset:24
	ds_read_b32 v109, v26 offset:28
	ds_read_b128 v[26:29], v34
	s_waitcnt lgkmcnt(0)
	v_mfma_f32_16x16x32_bf16 v[26:29], v[26:29], v[6:9], 0
	s_add_i32 s58, s30, s58
	s_add_i32 s31, s64, s91
	s_mul_i32 s59, s58, 31
	v_mfma_f32_16x16x32_bf16 v[26:29], v[30:33], v[2:5], v[26:29]
	ds_read_b128 v[30:33], v34 offset:512
	ds_read_b128 v[34:37], v35 offset:512
	s_addk_i32 s59, 0xff27
	s_lshl_b32 s31, s31, 13
	s_waitcnt lgkmcnt(1)
	v_mfma_f32_16x16x32_bf16 v[30:33], v[30:33], v[6:9], 0
	s_and_b32 s58, s31, 0xe000
	v_add_u32_e32 v118, s58, v61
	v_add_u32_e32 v123, v118, v55
	s_waitcnt lgkmcnt(0)
	v_mfma_f32_16x16x32_bf16 v[30:33], v[34:37], v[2:5], v[30:33]
	v_add_u32_e32 v34, s59, v46
	v_lshl_add_u32 v193, v34, 2, s84
	v_cndmask_b32_e64 v35, v194, v193, s[40:41]
	ds_read_b32 v110, v35
	v_add_u32_e32 v122, v118, v41
	ds_read_b128 v[118:121], v123
	v_cndmask_b32_e64 v35, v195, v193, s[42:43]
	ds_read_b32 v111, v35 offset:4
	v_cndmask_b32_e64 v35, v196, v193, s[44:45]
	ds_read_b32 v112, v35 offset:8
	v_cndmask_b32_e64 v35, v197, v193, s[46:47]
	ds_read_b32 v113, v35 offset:12
	v_cndmask_b32_e64 v35, v198, v193, s[48:49]
	ds_read_b32 v114, v35 offset:16
	v_cndmask_b32_e64 v35, v199, v193, s[50:51]
	ds_read_b32 v115, v35 offset:20
	v_cndmask_b32_e64 v35, v200, v193, s[52:53]
	v_cndmask_b32_e64 v34, v201, v193, s[54:55]
	ds_read_b32 v116, v35 offset:24
	ds_read_b32 v117, v34 offset:28
	ds_read_b128 v[34:37], v122
	s_waitcnt lgkmcnt(0)
	v_mfma_f32_16x16x32_bf16 v[34:37], v[34:37], v[6:9], 0
	s_cmp_eq_u32 s80, s64
	v_mfma_f32_16x16x32_bf16 v[34:37], v[118:121], v[2:5], v[34:37]
	ds_read_b128 v[118:121], v122 offset:512
	ds_read_b128 v[122:125], v123 offset:512
	s_waitcnt lgkmcnt(0)
	s_barrier
	s_waitcnt lgkmcnt(1)
	v_mfma_f32_16x16x32_bf16 v[6:9], v[118:121], v[6:9], 0
	s_waitcnt lgkmcnt(0)
	v_mfma_f32_16x16x32_bf16 v[2:5], v[122:125], v[2:5], v[6:9]
	s_cbranch_scc1 .LBB0_453
	s_lshl_b32 s31, s64, 17
	s_add_u32 s58, s21, s31
	s_addc_u32 s59, s83, 0
	s_nop 1
	v_lshl_add_u64 v[6:7], s[58:59], 0, v[50:51]
	v_lshl_add_u64 v[6:7], v[6:7], 0, s[22:23]
	s_lshl_b32 s31, s64, 13
	v_lshl_add_u64 v[6:7], v[6:7], 0, v[0:1]
	s_mov_b64 s[58:59], 0x100000
	s_and_b32 s31, s31, 0xe000
	v_lshl_add_u64 v[6:7], v[6:7], 0, s[58:59]
	s_add_i32 m0, s86, s31
	s_nop 0
	global_load_lds_dwordx4 v[6:7], off

; #define LAS __attribute__((address_space(3)))
; __device__ __forceinline__ unsigned cvt_pk_bf16(float lo, float hi) { unsigned r; asm volatile("v_cvt_pk_bf16_f32 %0, %1, %2" : "=v"(r) : "v"(lo), "v"(hi)); return r; }
; __device__ __forceinline__ float bf_lo(unsigned w) { return __uint_as_float(w << 16); }
; __device__ __forceinline__ float bf_hi(unsigned w) { return __uint_as_float(w & 0xffff0000u); }
; __device__ __forceinline__ float fast_exp2(float x) { return __builtin_amdgcn_exp2f(x); }
; #define SCHED_FENCE() __builtin_amdgcn_sched_barrier(0)
; #define ATT_BAR() do { asm volatile("s_waitcnt lgkmcnt(0)" ::: "memory"); __builtin_amdgcn_s_barrier(); asm volatile("" ::: "memory"); } while (0)
; __device__ __forceinline__ void attn_phase(const bf16_t* Q, const bf16_t* Kb, const bf16_t* VTa, const float* rpb, bf16_t* Y, LAS unsigned char* lds, int bx, int G, int tid, int wave, int lane) {
;     ...
;             LAS float* ml = (LAS float*)(lds + 131072 + 2048) + (size_t)(g * 64 + lane) * 2;
;             LAS u32x2* ol = (LAS u32x2*)(lds + 131072 + 4096) + (size_t)(g * 64 + lane) * 4;
;             if (hf == 1) {
; #pragma unroll
;                 for (int dt = 0; dt < 4; ++dt) { u32x2 w; w.x = cvt_pk_bf16(o[dt][0], o[dt][1]); w.y = cvt_pk_bf16(o[dt][2], o[dt][3]); ol[dt] = w; }
;                 ml[0] = mx; ml[1] = l;
;             }
;             ATT_BAR();
;             if (hf == 0) {
;                 const float m1 = ml[0], l1 = ml[1];
;                 const float m = fmaxf(mx, m1), sc0 = fast_exp2((mx - m) * 1.4426950409f), sc1 = fast_exp2((m1 - m) * 1.4426950409f);
;                 const float inv = 1.0f / (l * sc0 + l1 * sc1);
;                 bf16_t* yp = Y + (size_t)(r * 64 + c) * 2048 + 1024 + h * 64 + 4 * fq;
; #pragma unroll
;                 for (int dt = 0; dt < 4; ++dt) { const u32x2 pw = ol[dt]; const f32x4 o1 = {bf_lo(pw.x), bf_hi(pw.x), bf_lo(pw.y), bf_hi(pw.y)}; const f32x4 v = (o[dt] * sc0 + o1 * sc1) * inv;
;                     u32x2 w; w.x = cvt_pk_bf16(v[0], v[1]); w.y = cvt_pk_bf16(v[2], v[3]); *(u32x2*)(yp + 16 * dt) = w; }
;             }
;             ATT_BAR();
;             SCHED_FENCE();
;             if (newrow) ATT_V_PIECE(h, rs + 8, wave);
;             SCHED_FENCE();
.LBB0_459:
	s_waitcnt lgkmcnt(0)
	s_barrier
	s_mov_b32 s32, 0
	s_and_b64 vcc, exec, s[60:61]
	s_cbranch_vccnz .Latt_novp
	s_lshl_b32 s31, s64, 13
	s_lshl_b32 s60, s64, 7
	s_mov_b32 s61, s23
	s_and_b32 s31, s31, 0xe000
	v_lshl_add_u64 v[228:229], v[96:97], 0, s[60:61]
	s_mov_b64 s[60:61], 0x400
	s_add_i32 m0, s88, s31
	v_lshl_add_u64 v[228:229], v[228:229], 0, s[60:61]
	global_load_lds_dwordx4 v[228:229], off
	s_mov_b32 s32, 1
.Latt_novp:
	v_cndmask_b32_e64 v26, 0, 1, s[12:13]
	v_cmp_ne_u32_e64 s[56:57], 1, v26
	s_andn2_b64 vcc, exec, s[12:13]
	s_cbranch_vccnz .LBB0_461
	v_add_u32_e32 v26, 0, v57
	v_add_u32_e32 v26, 0x20800, v26
	ds_read_b64 v[26:27], v26
	v_add_u32_e32 v28, 0, v59
	v_add_u32_e32 v63, 0x21000, v28
	v_max_f32_e32 v35, v32, v32
	ds_read_b64 v[28:29], v63
	ds_read_b64 v[222:223], v63 offset:8
	ds_read_b64 v[224:225], v63 offset:16
	ds_read_b64 v[226:227], v63 offset:24
	s_waitcnt lgkmcnt(3)
	v_max_f32_e32 v36, v26, v26
	v_max_f32_e32 v35, v35, v36
	v_sub_f32_e32 v32, v32, v35
	v_sub_f32_e32 v26, v26, v35
	v_mul_f32_e32 v32, 0x3fb8aa3b, v32
	v_mul_f32_e32 v26, 0x3fb8aa3b, v26
	v_exp_f32_e32 v36, v32
	v_exp_f32_e32 v37, v26
	v_mov_b32_e32 v26, v33
	v_ashrrev_i32_e32 v99, 31, v98
	v_pk_mul_f32 v[26:27], v[26:27], v[36:37]
	s_nop 0
	v_add_f32_e32 v26, v26, v27
	v_div_scale_f32 v27, vcc, v26, v26, 1.0
	v_rcp_f32_e32 v32, v27
	v_mov_b32_e32 v100, v37
	v_fma_f32 v33, -v27, v32, 1.0
	v_fmac_f32_e32 v32, v33, v32
	v_div_scale_f32 v33, vcc, 1.0, v26, 1.0
	v_mul_f32_e32 v35, v33, v32
	v_fma_f32 v65, -v27, v35, v33
	v_fmac_f32_e32 v35, v65, v32
	v_fma_f32 v27, -v27, v35, v33
	v_div_fmas_f32 v27, v27, v32, v35
	v_lshlrev_b32_e32 v32, 16, v28
	v_and_b32_e32 v33, 0xffff0000, v28
	v_lshlrev_b32_e32 v28, 16, v29
	v_and_b32_e32 v29, 0xffff0000, v29
	v_pk_mul_f32 v[28:29], v[100:101], v[28:29] op_sel_hi:[0,1]
	v_pk_mul_f32 v[32:33], v[100:101], v[32:33] op_sel_hi:[0,1]
	v_div_fixup_f32 v26, v27, v26, 1.0
	v_pk_fma_f32 v[22:23], v[22:23], v[36:37], v[32:33] op_sel_hi:[1,0,1]
	v_pk_fma_f32 v[24:25], v[24:25], v[36:37], v[28:29] op_sel_hi:[1,0,1]
	v_pk_mul_f32 v[22:23], v[26:27], v[22:23] op_sel_hi:[0,1]
	v_pk_mul_f32 v[24:25], v[26:27], v[24:25] op_sel_hi:[0,1]
	v_cvt_pk_bf16_f32 v22, v22, v23
	v_cvt_pk_bf16_f32 v23, v24, v25
	v_lshlrev_b64 v[28:29], 12, v[98:99]
	v_lshl_add_u64 v[28:29], v[94:95], 0, v[28:29]
	v_and_b32_e32 v238, 16, v241
	v_lshrrev_b32_e32 v239, 1, v238
	v_add_u32_e32 v238, v238, v239
	v_mov_b32_e32 v239, 0
	v_lshl_add_u64 v[28:29], v[28:29], 0, v[238:239]
	s_waitcnt lgkmcnt(2)
	v_lshlrev_b32_e32 v228, 16, v222
	v_and_b32_e32 v229, 0xffff0000, v222
	v_lshlrev_b32_e32 v230, 16, v223
	v_and_b32_e32 v231, 0xffff0000, v223
	v_pk_mul_f32 v[230:231], v[100:101], v[230:231] op_sel_hi:[0,1]
	v_pk_mul_f32 v[228:229], v[100:101], v[228:229] op_sel_hi:[0,1]
	v_pk_fma_f32 v[18:19], v[18:19], v[36:37], v[228:229] op_sel_hi:[1,0,1]
	v_pk_fma_f32 v[20:21], v[20:21], v[36:37], v[230:231] op_sel_hi:[1,0,1]
	v_pk_mul_f32 v[18:19], v[26:27], v[18:19] op_sel_hi:[0,1]
	v_pk_mul_f32 v[20:21], v[26:27], v[20:21] op_sel_hi:[0,1]
	v_cvt_pk_bf16_f32 v24, v18, v19
	v_cvt_pk_bf16_f32 v25, v20, v21
	s_nop 1
	v_permlane16_swap_b32 v22, v24
	v_permlane16_swap_b32 v23, v25
	global_store_dwordx4 v[28:29], v[22:25], off offset:2048
	s_waitcnt lgkmcnt(1)
	v_lshlrev_b32_e32 v18, 16, v224
	v_and_b32_e32 v19, 0xffff0000, v224
	v_lshlrev_b32_e32 v20, 16, v225
	v_and_b32_e32 v21, 0xffff0000, v225
	v_pk_mul_f32 v[20:21], v[100:101], v[20:21] op_sel_hi:[0,1]
	v_pk_mul_f32 v[18:19], v[100:101], v[18:19] op_sel_hi:[0,1]
	v_pk_fma_f32 v[14:15], v[14:15], v[36:37], v[18:19] op_sel_hi:[1,0,1]
	v_pk_fma_f32 v[16:17], v[16:17], v[36:37], v[20:21] op_sel_hi:[1,0,1]
	v_pk_mul_f32 v[14:15], v[26:27], v[14:15] op_sel_hi:[0,1]
	v_pk_mul_f32 v[16:17], v[26:27], v[16:17] op_sel_hi:[0,1]
	v_cvt_pk_bf16_f32 v14, v14, v15
	v_cvt_pk_bf16_f32 v15, v16, v17
	s_waitcnt lgkmcnt(0)
	v_lshlrev_b32_e32 v228, 16, v226
	v_and_b32_e32 v229, 0xffff0000, v226
	v_lshlrev_b32_e32 v230, 16, v227
	v_and_b32_e32 v231, 0xffff0000, v227
	v_pk_mul_f32 v[228:229], v[100:101], v[228:229] op_sel_hi:[0,1]
	v_pk_mul_f32 v[230:231], v[100:101], v[230:231] op_sel_hi:[0,1]
	v_pk_fma_f32 v[10:11], v[10:11], v[36:37], v[228:229] op_sel_hi:[1,0,1]
	v_pk_fma_f32 v[12:13], v[12:13], v[36:37], v[230:231] op_sel_hi:[1,0,1]
	v_pk_mul_f32 v[10:11], v[26:27], v[10:11] op_sel_hi:[0,1]
	v_pk_mul_f32 v[12:13], v[26:27], v[12:13] op_sel_hi:[0,1]
	v_cvt_pk_bf16_f32 v16, v10, v11
	v_cvt_pk_bf16_f32 v17, v12, v13
	s_nop 1
	v_permlane16_swap_b32 v14, v16
	v_permlane16_swap_b32 v15, v17
	global_store_dwordx4 v[28:29], v[14:17], off offset:2112
.LBB0_461:
	s_waitcnt lgkmcnt(0)
	s_barrier
.LBB0_463:
	s_add_i32 s30, s30, -1
	s_add_i32 s94, s94, 1
	s_cmp_eq_u32 s30, 0
	s_cbranch_scc1 .LBB0_465
	v_mov_b32_e32 v98, v30
	s_branch .LBB0_451
.LBB0_465:
	s_or_b32 s20, s93, 7
	s_max_i32 s30, s20, 4
	s_add_i32 s30, s30, -4
	s_min_u32 s30, s30, 0x78
	s_add_i32 s31, s30, s85
	s_sub_i32 s60, s31, s20
	s_lshl_b32 s31, s31, 13
	v_mad_u64_u32 v[10:11], s[60:61], s60, 31, v[46:47]
	s_and_b32 s31, s31, 0xe000
	s_and_b32 s26, s12, 2
	s_add_i32 s26, s26, s32
	s_cmp_lg_u32 s26, 0
	s_cbranch_scc1 .Ltop0_a
	s_waitcnt vmcnt(0)
	s_branch .Ltop0_d

; #define LAS __attribute__((address_space(3)))
; #define MFMA16(a, b, c) __builtin_amdgcn_mfma_f32_16x16x32_bf16((a), (b), (c), 0, 0, 0)
; __device__ __forceinline__ int att_fk(int key) { return ((key >> 3) & 3) + 4 * ((key >> 1) & 1); }
; #define ATT_BAR() do { asm volatile("s_waitcnt lgkmcnt(0)" ::: "memory"); __builtin_amdgcn_s_barrier(); asm volatile("" ::: "memory"); } while (0)
; __device__ __forceinline__ void attn_phase(const bf16_t* Q, const bf16_t* Kb, const bf16_t* VTa, const float* rpb, bf16_t* Y, LAS unsigned char* lds, int bx, int G, int tid, int wave, int lane) {
;     ...
;             asm volatile("s_waitcnt vmcnt(1)" ::: "memory");
;             ATT_BAR();
;             f32x4 s[4][2];
;             float mx = -3.0e38f;
; #pragma unroll
;             for (int ii = 0; ii < 4; ++ii) {
;                 const int i = 4 * hf + ii, dr = rs + i - r + 7;
;                 float bia[8];
; #pragma unroll
;                 for (int j = 0; j < 8; ++j) bia[j] = rl[((unsigned)(j - wlo) < (unsigned)wwd) ? dr * 31 + dci0 + j : 480];
; #pragma unroll
;                 for (int ta = 0; ta < 2; ++ta) {
;                     const int key = cs + 8 * (fr >> 2) + 4 * ta + (fr & 3), fk = att_fk(key);
;                     const LAS unsigned char* kp = KL + ((rs + i) & 7) * 8192 + key * 128;
;                     const bf16x8 kf0 = *(const LAS bf16x8*)(kp + ((fq ^ fk) << 4)), kf1 = *(const LAS bf16x8*)(kp + (((4 + fq) ^ fk) << 4));
;                     f32x4 a = {0.f, 0.f, 0.f, 0.f};
;                     a = MFMA16(kf0, qf0, a); a = MFMA16(kf1, qf1, a);
; #pragma unroll
;                     for (int idx = 0; idx < 4; ++idx) { a[idx] += bia[4 * ta + idx]; mx = fmaxf(mx, a[idx]); }
;                     s[ii][ta] = a;
;                 }
;             }
.Ltop0_d:
	v_lshl_add_u32 v190, v10, 2, s84
	v_cndmask_b32_e64 v11, v194, v190, s[40:41]
	v_add_u32_e32 v14, s31, v61
	s_waitcnt lgkmcnt(0)
	s_barrier
	v_add_u32_e32 v27, v14, v55
	ds_read_b32 v18, v11
	v_add_u32_e32 v26, v14, v41
	ds_read_b128 v[14:17], v27
	v_cndmask_b32_e64 v11, v195, v190, s[42:43]
	ds_read_b32 v19, v11 offset:4
	v_cndmask_b32_e64 v11, v196, v190, s[44:45]
	ds_read_b32 v20, v11 offset:8
	v_cndmask_b32_e64 v11, v197, v190, s[46:47]
	ds_read_b32 v21, v11 offset:12
	v_cndmask_b32_e64 v11, v198, v190, s[48:49]
	ds_read_b32 v22, v11 offset:16
	v_cndmask_b32_e64 v11, v199, v190, s[50:51]
	ds_read_b32 v23, v11 offset:20
	v_cndmask_b32_e64 v11, v200, v190, s[52:53]
	v_cndmask_b32_e64 v10, v201, v190, s[54:55]
	ds_read_b32 v24, v11 offset:24
	ds_read_b32 v25, v10 offset:28
	ds_read_b128 v[10:13], v26
	s_waitcnt lgkmcnt(0)
	v_mfma_f32_16x16x32_bf16 v[10:13], v[10:13], v[6:9], 0
	s_add_i32 s31, s30, s89
	s_sub_i32 s60, s31, s20
	s_lshl_b32 s31, s31, 13
	v_mfma_f32_16x16x32_bf16 v[14:17], v[14:17], v[2:5], v[10:13]
	s_and_b32 s31, s31, 0xe000
	s_nop 6
	v_add_f32_e32 v13, v18, v14
	v_add_f32_e32 v12, v19, v15
	v_max3_f32 v14, v13, s6, v12
	v_add_f32_e32 v11, v20, v16
	v_add_f32_e32 v10, v21, v17
	v_max3_f32 v28, v14, v11, v10
	ds_read_b128 v[14:17], v26 offset:512
	ds_read_b128 v[18:21], v27 offset:512
	s_waitcnt lgkmcnt(1)
	v_mfma_f32_16x16x32_bf16 v[14:17], v[14:17], v[6:9], 0
	s_waitcnt lgkmcnt(0)
	v_mfma_f32_16x16x32_bf16 v[18:21], v[18:21], v[2:5], v[14:17]
	s_nop 7
	v_add_f32_e32 v17, v22, v18
	v_add_f32_e32 v16, v23, v19
	v_max3_f32 v18, v28, v17, v16
	v_add_f32_e32 v15, v24, v20
	v_add_f32_e32 v14, v25, v21
	v_max3_f32 v26, v18, v15, v14
	v_mad_u64_u32 v[18:19], s[60:61], s60, 31, v[46:47]
	v_lshl_add_u32 v191, v18, 2, s84
	v_cndmask_b32_e64 v19, v194, v191, s[40:41]
	v_add_u32_e32 v22, s31, v61
	v_add_u32_e32 v63, v22, v55
	ds_read_b32 v27, v19
	v_add_u32_e32 v37, v22, v41
	ds_read_b128 v[22:25], v63
	v_cndmask_b32_e64 v19, v195, v191, s[42:43]
	ds_read_b32 v28, v19 offset:4
	v_cndmask_b32_e64 v19, v196, v191, s[44:45]
	ds_read_b32 v29, v19 offset:8
	v_cndmask_b32_e64 v19, v197, v191, s[46:47]
	ds_read_b32 v30, v19 offset:12
	v_cndmask_b32_e64 v19, v198, v191, s[48:49]
	ds_read_b32 v32, v19 offset:16
	v_cndmask_b32_e64 v19, v199, v191, s[50:51]
	ds_read_b32 v33, v19 offset:20
	v_cndmask_b32_e64 v19, v200, v191, s[52:53]
	v_cndmask_b32_e64 v18, v201, v191, s[54:55]
	ds_read_b32 v35, v19 offset:24
	ds_read_b32 v36, v18 offset:28
	ds_read_b128 v[18:21], v37
	s_waitcnt lgkmcnt(0)
	v_mfma_f32_16x16x32_bf16 v[18:21], v[18:21], v[6:9], 0
	s_add_i32 s31, s30, s90
	s_sub_i32 s60, s31, s20
	s_lshl_b32 s31, s31, 13
	v_mfma_f32_16x16x32_bf16 v[22:25], v[22:25], v[2:5], v[18:21]
	s_and_b32 s31, s31, 0xe000
	v_add_u32_e32 v73, s31, v61
	v_add_u32_e32 v75, v73, v41
	v_add_u32_e32 v73, v73, v55
	s_add_i32 s31, s30, s91
	s_nop 2
	v_add_f32_e32 v22, v27, v22
	v_add_f32_e32 v21, v28, v23
	v_max3_f32 v18, v26, v22, v21
	v_add_f32_e32 v20, v29, v24
	v_add_f32_e32 v19, v30, v25
	ds_read_b128 v[24:27], v37 offset:512
	ds_read_b128 v[92:95], v63 offset:512
	s_waitcnt lgkmcnt(1)
	v_mfma_f32_16x16x32_bf16 v[24:27], v[24:27], v[6:9], 0
	v_max3_f32 v18, v18, v20, v19
	s_waitcnt lgkmcnt(0)
	v_mfma_f32_16x16x32_bf16 v[24:27], v[92:95], v[2:5], v[24:27]
	ds_read_b128 v[92:95], v73
	s_nop 6
	v_add_f32_e32 v23, v32, v24
	v_add_f32_e32 v28, v33, v25
	v_mad_u64_u32 v[24:25], s[60:61], s60, 31, v[46:47]
	v_lshl_add_u32 v192, v24, 2, s84
	v_cndmask_b32_e64 v25, v194, v192, s[40:41]
	ds_read_b32 v32, v25
	v_cndmask_b32_e64 v25, v195, v192, s[42:43]
	ds_read_b32 v33, v25 offset:4
	v_cndmask_b32_e64 v25, v196, v192, s[44:45]
	v_add_f32_e32 v29, v35, v26
	ds_read_b32 v35, v25 offset:8
	v_cndmask_b32_e64 v25, v197, v192, s[46:47]
	v_add_f32_e32 v30, v36, v27
	ds_read_b32 v36, v25 offset:12
	v_cndmask_b32_e64 v25, v198, v192, s[48:49]
	ds_read_b32 v37, v25 offset:16
	v_cndmask_b32_e64 v25, v199, v192, s[50:51]
	ds_read_b32 v63, v25 offset:20
	v_cndmask_b32_e64 v25, v200, v192, s[52:53]
	v_cndmask_b32_e64 v24, v201, v192, s[54:55]
	ds_read_b32 v65, v25 offset:24
	ds_read_b32 v71, v24 offset:28
	ds_read_b128 v[24:27], v75
	s_waitcnt lgkmcnt(0)
	v_mfma_f32_16x16x32_bf16 v[24:27], v[24:27], v[6:9], 0
	s_sub_i32 s60, s31, s20
	s_lshl_b32 s31, s31, 13
	s_and_b32 s31, s31, 0xe000
	v_mfma_f32_16x16x32_bf16 v[24:27], v[92:95], v[2:5], v[24:27]
	v_add_u32_e32 v89, s31, v61
	v_add_u32_e32 v91, v89, v41
	v_add_u32_e32 v89, v89, v55
	v_max3_f32 v18, v18, v23, v28
	v_max3_f32 v18, v18, v29, v30
	s_nop 2
	v_add_f32_e32 v32, v32, v24
	v_add_f32_e32 v33, v33, v25
	v_add_f32_e32 v35, v35, v26
	v_add_f32_e32 v36, v36, v27
	ds_read_b128 v[24:27], v75 offset:512
	ds_read_b128 v[92:95], v73 offset:512
	s_waitcnt lgkmcnt(1)
	v_mfma_f32_16x16x32_bf16 v[24:27], v[24:27], v[6:9], 0
	v_max3_f32 v18, v18, v32, v33
	v_max3_f32 v18, v18, v35, v36
	s_waitcnt lgkmcnt(0)
	v_mfma_f32_16x16x32_bf16 v[24:27], v[92:95], v[2:5], v[24:27]
	ds_read_b128 v[92:95], v89
	s_nop 6
	v_add_f32_e32 v37, v37, v24
	v_add_f32_e32 v63, v63, v25
	v_mad_u64_u32 v[24:25], s[60:61], s60, 31, v[46:47]
	v_lshl_add_u32 v193, v24, 2, s84
	v_cndmask_b32_e64 v25, v194, v193, s[40:41]
	ds_read_b32 v73, v25
	v_cndmask_b32_e64 v25, v195, v193, s[42:43]
	ds_read_b32 v75, v25 offset:4
	v_cndmask_b32_e64 v25, v196, v193, s[44:45]
	ds_read_b32 v77, v25 offset:8
	v_cndmask_b32_e64 v25, v197, v193, s[46:47]
	ds_read_b32 v79, v25 offset:12
	v_cndmask_b32_e64 v25, v198, v193, s[48:49]
	ds_read_b32 v81, v25 offset:16
	v_cndmask_b32_e64 v25, v199, v193, s[50:51]
	ds_read_b32 v83, v25 offset:20
	v_cndmask_b32_e64 v25, v200, v193, s[52:53]
	v_cndmask_b32_e64 v24, v201, v193, s[54:55]
	v_add_f32_e32 v65, v65, v26
	v_add_f32_e32 v71, v71, v27
	ds_read_b32 v85, v25 offset:24
	ds_read_b32 v87, v24 offset:28
	ds_read_b128 v[24:27], v91
	s_waitcnt lgkmcnt(0)
	v_mfma_f32_16x16x32_bf16 v[24:27], v[24:27], v[6:9], 0
	v_max3_f32 v18, v18, v37, v63
	v_max3_f32 v18, v18, v65, v71
	v_mfma_f32_16x16x32_bf16 v[24:27], v[92:95], v[2:5], v[24:27]
	s_nop 7
	v_add_f32_e32 v73, v73, v24
	v_add_f32_e32 v75, v75, v25
	v_add_f32_e32 v77, v77, v26
	v_add_f32_e32 v79, v79, v27
	ds_read_b128 v[24:27], v91 offset:512
	ds_read_b128 v[92:95], v89 offset:512
	s_waitcnt lgkmcnt(1)
	v_mfma_f32_16x16x32_bf16 v[6:9], v[24:27], v[6:9], 0
	v_max3_f32 v18, v18, v73, v75
	v_max3_f32 v18, v18, v77, v79
	s_waitcnt lgkmcnt(0)
	s_waitcnt lgkmcnt(0)
	v_mfma_f32_16x16x32_bf16 v[2:5], v[92:95], v[2:5], v[6:9]
	s_barrier
; __device__ __forceinline__ float fast_exp2(float x) { return __builtin_amdgcn_exp2f(x); }
; __device__ __forceinline__ u32x4 pack8(f32x4 a, f32x4 b) { u32x4 w; w.x = cvt_pk_bf16(a[0], a[1]); w.y = cvt_pk_bf16(a[2], a[3]); w.z = cvt_pk_bf16(b[0], b[1]); w.w = cvt_pk_bf16(b[2], b[3]); return w; }
; #define SCHED_FENCE() __builtin_amdgcn_sched_barrier(0)
; #define ATT_BAR() do { asm volatile("s_waitcnt lgkmcnt(0)" ::: "memory"); __builtin_amdgcn_s_barrier(); asm volatile("" ::: "memory"); } while (0)
; __device__ __forceinline__ void attn_phase(const bf16_t* Q, const bf16_t* Kb, const bf16_t* VTa, const float* rpb, bf16_t* Y, LAS unsigned char* lds, int bx, int G, int tid, int wave, int lane) {
;     ...
;             mx = fmaxf(mx, __shfl_xor(mx, 16)); mx = fmaxf(mx, __shfl_xor(mx, 32));
;             float l = 0.f;
;             bf16x8 pb[4];
; #pragma unroll
;             for (int ii = 0; ii < 4; ++ii) {
;                 f32x4 p0, p1;
; #pragma unroll
;                 for (int idx = 0; idx < 4; ++idx) { p0[idx] = fast_exp2((s[ii][0][idx] - mx) * 1.4426950409f); p1[idx] = fast_exp2((s[ii][1][idx] - mx) * 1.4426950409f); }
;                 l += (p0[0] + p0[1]) + (p0[2] + p0[3]) + (p1[0] + p1[1]) + (p1[2] + p1[3]);
;                 const u32x4 pw = pack8(p0, p1); pb[ii] = __builtin_bit_cast(bf16x8, pw);
;             }
;             l += __shfl_xor(l, 16); l += __shfl_xor(l, 32);
;             SCHED_FENCE();
;             if (newrow) asm volatile("s_waitcnt vmcnt(3)" ::: "memory"); else if (has_next) asm volatile("s_waitcnt vmcnt(2)" ::: "memory"); else asm volatile("s_waitcnt vmcnt(0)" ::: "memory");
;             ATT_BAR();
	s_nop 6
	v_add_f32_e32 v24, v81, v2
	v_add_f32_e32 v25, v83, v3
	v_max3_f32 v2, v18, v24, v25
	v_add_f32_e32 v26, v85, v4
	v_add_f32_e32 v27, v87, v5
	v_max3_f32 v2, v2, v26, v27
	ds_bpermute_b32 v3, v31, v2
	s_waitcnt lgkmcnt(0)
	v_max_f32_e32 v3, v3, v3
	v_max_f32_e32 v2, v2, v3
	ds_bpermute_b32 v3, v34, v2
	s_waitcnt lgkmcnt(0)
	v_max_f32_e32 v3, v3, v3
	v_max_f32_e32 v18, v2, v3
	v_sub_f32_e32 v3, v17, v18
	v_sub_f32_e32 v4, v12, v18
	v_sub_f32_e32 v5, v16, v18
	v_mul_f32_e32 v3, 0x3fb8aa3b, v3
	v_mul_f32_e32 v4, 0x3fb8aa3b, v4
	v_mul_f32_e32 v5, 0x3fb8aa3b, v5
	v_sub_f32_e32 v2, v13, v18
	v_exp_f32_e32 v6, v3
	v_exp_f32_e32 v3, v4
	v_exp_f32_e32 v4, v5
	v_sub_f32_e32 v5, v11, v18
	v_sub_f32_e32 v8, v10, v18
	v_mul_f32_e32 v2, 0x3fb8aa3b, v2
	v_mul_f32_e32 v5, 0x3fb8aa3b, v5
	v_mul_f32_e32 v8, 0x3fb8aa3b, v8
	v_exp_f32_e32 v2, v2
	v_exp_f32_e32 v5, v5
	v_sub_f32_e32 v7, v15, v18
	v_exp_f32_e32 v8, v8
	v_sub_f32_e32 v9, v14, v18
	v_mul_f32_e32 v7, 0x3fb8aa3b, v7
	v_mul_f32_e32 v9, 0x3fb8aa3b, v9
	v_exp_f32_e32 v7, v7
	v_exp_f32_e32 v9, v9
	v_add_f32_e32 v10, v2, v3
	v_add_f32_e32 v11, v5, v8
	v_add_f32_e32 v10, v10, v11
	v_add_f32_e32 v11, v6, v4
	v_add_f32_e32 v10, v11, v10
	v_add_f32_e32 v11, v7, v9
	v_cvt_pk_bf16_f32 v2, v2, v3
	v_cvt_pk_bf16_f32 v3, v5, v8
	v_cvt_pk_bf16_f32 v4, v6, v4
	v_cvt_pk_bf16_f32 v5, v7, v9
	v_sub_f32_e32 v7, v23, v18
	v_mul_f32_e32 v7, 0x3fb8aa3b, v7
	v_add_f32_e32 v10, v11, v10
	v_sub_f32_e32 v6, v22, v18
	v_exp_f32_e32 v8, v7
	v_sub_f32_e32 v7, v21, v18
	v_sub_f32_e32 v11, v20, v18
	v_sub_f32_e32 v13, v19, v18
	v_mul_f32_e32 v6, 0x3fb8aa3b, v6
	v_mul_f32_e32 v7, 0x3fb8aa3b, v7
	v_sub_f32_e32 v9, v28, v18
	v_mul_f32_e32 v11, 0x3fb8aa3b, v11
	v_mul_f32_e32 v13, 0x3fb8aa3b, v13
	v_exp_f32_e32 v6, v6
	v_exp_f32_e32 v7, v7
	v_mul_f32_e32 v9, 0x3fb8aa3b, v9
	v_exp_f32_e32 v11, v11
	v_sub_f32_e32 v12, v29, v18
	v_exp_f32_e32 v13, v13
	v_sub_f32_e32 v14, v30, v18
	v_exp_f32_e32 v9, v9
	v_mul_f32_e32 v12, 0x3fb8aa3b, v12
	v_mul_f32_e32 v14, 0x3fb8aa3b, v14
	v_exp_f32_e32 v12, v12
	v_exp_f32_e32 v14, v14
	v_add_f32_e32 v15, v6, v7
	v_add_f32_e32 v16, v11, v13
	v_add_f32_e32 v15, v15, v16
	v_add_f32_e32 v16, v8, v9
	v_add_f32_e32 v15, v16, v15
	v_add_f32_e32 v16, v12, v14
	v_add_f32_e32 v10, 0, v10
	v_add_f32_e32 v15, v16, v15
	v_add_f32_e32 v10, v15, v10
	v_cvt_pk_bf16_f32 v6, v6, v7
	v_cvt_pk_bf16_f32 v7, v11, v13
	v_sub_f32_e32 v11, v32, v18
	v_sub_f32_e32 v13, v33, v18
	v_sub_f32_e32 v15, v35, v18
	v_sub_f32_e32 v17, v36, v18
	v_cvt_pk_bf16_f32 v8, v8, v9
	v_cvt_pk_bf16_f32 v9, v12, v14
	v_mul_f32_e32 v11, 0x3fb8aa3b, v11
	v_sub_f32_e32 v12, v37, v18
	v_mul_f32_e32 v13, 0x3fb8aa3b, v13
	v_sub_f32_e32 v14, v63, v18
	v_mul_f32_e32 v15, 0x3fb8aa3b, v15
	v_mul_f32_e32 v17, 0x3fb8aa3b, v17
	v_exp_f32_e32 v11, v11
	v_mul_f32_e32 v12, 0x3fb8aa3b, v12
	v_exp_f32_e32 v13, v13
	v_mul_f32_e32 v14, 0x3fb8aa3b, v14
	v_exp_f32_e32 v15, v15
	v_sub_f32_e32 v16, v65, v18
	v_exp_f32_e32 v17, v17
	v_sub_f32_e32 v19, v71, v18
	v_exp_f32_e32 v12, v12
	v_exp_f32_e32 v14, v14
	v_mul_f32_e32 v16, 0x3fb8aa3b, v16
	v_mul_f32_e32 v19, 0x3fb8aa3b, v19
	v_exp_f32_e32 v16, v16
	v_exp_f32_e32 v19, v19
	v_add_f32_e32 v20, v11, v13
	v_add_f32_e32 v21, v15, v17
	v_add_f32_e32 v20, v20, v21
	v_add_f32_e32 v21, v12, v14
	v_add_f32_e32 v20, v21, v20
	v_add_f32_e32 v21, v16, v19
	v_add_f32_e32 v20, v21, v20
	v_sub_f32_e32 v21, v24, v18
	v_mul_f32_e32 v21, 0x3fb8aa3b, v21
	v_add_f32_e32 v10, v20, v10
	v_sub_f32_e32 v20, v73, v18
	v_exp_f32_e32 v22, v21
	v_sub_f32_e32 v21, v75, v18
	v_sub_f32_e32 v23, v25, v18
	v_sub_f32_e32 v24, v77, v18
	v_sub_f32_e32 v25, v26, v18
	v_sub_f32_e32 v26, v79, v18
	v_mul_f32_e32 v20, 0x3fb8aa3b, v20
	v_mul_f32_e32 v21, 0x3fb8aa3b, v21
	v_mul_f32_e32 v24, 0x3fb8aa3b, v24
	v_mul_f32_e32 v26, 0x3fb8aa3b, v26
	v_exp_f32_e32 v20, v20
	v_exp_f32_e32 v21, v21
	v_mul_f32_e32 v23, 0x3fb8aa3b, v23
	v_exp_f32_e32 v24, v24
	v_exp_f32_e32 v26, v26
	v_sub_f32_e32 v27, v27, v18
	v_exp_f32_e32 v23, v23
	v_mul_f32_e32 v25, 0x3fb8aa3b, v25
	v_mul_f32_e32 v27, 0x3fb8aa3b, v27
	v_exp_f32_e32 v25, v25
	v_exp_f32_e32 v27, v27
	v_add_f32_e32 v28, v20, v21
	v_add_f32_e32 v29, v24, v26
	v_add_f32_e32 v28, v28, v29
	v_add_f32_e32 v29, v22, v23
	v_add_f32_e32 v28, v29, v28
	v_add_f32_e32 v29, v25, v27
	v_add_f32_e32 v28, v29, v28
	v_add_f32_e32 v28, v28, v10
	ds_bpermute_b32 v29, v31, v28
	v_cvt_pk_bf16_f32 v10, v11, v13
	v_cvt_pk_bf16_f32 v11, v15, v17
	v_cvt_pk_bf16_f32 v12, v12, v14
	v_cvt_pk_bf16_f32 v13, v16, v19
	s_waitcnt lgkmcnt(0)
	v_add_f32_e32 v14, v28, v29
	ds_bpermute_b32 v15, v34, v14
	v_cvt_pk_bf16_f32 v20, v20, v21
	v_cvt_pk_bf16_f32 v21, v24, v26
	v_cvt_pk_bf16_f32 v22, v22, v23
	v_cvt_pk_bf16_f32 v23, v25, v27
	s_waitcnt lgkmcnt(0)
	v_add_f32_e32 v19, v14, v15
	s_or_b32 s30, s30, s87
	s_lshl_b32 s30, s30, 13
	s_waitcnt vmcnt(0)
	s_and_b32 s31, s30, 0xe000
	s_waitcnt lgkmcnt(0)
	s_barrier
; #define LAS __attribute__((address_space(3)))
; __device__ __forceinline__ unsigned cvt_pk_bf16(float lo, float hi) { unsigned r; asm volatile("v_cvt_pk_bf16_f32 %0, %1, %2" : "=v"(r) : "v"(lo), "v"(hi)); return r; }
; #define MFMA16(a, b, c) __builtin_amdgcn_mfma_f32_16x16x32_bf16((a), (b), (c), 0, 0, 0)
; __device__ __forceinline__ int att_fv(int dh) { return (dh >> 1) & 7; }
; __device__ __forceinline__ void attn_phase(const bf16_t* Q, const bf16_t* Kb, const bf16_t* VTa, const float* rpb, bf16_t* Y, LAS unsigned char* lds, int bx, int G, int tid, int wave, int lane) {
;     ...
;             f32x4 o[4];
; #pragma unroll
;             for (int dt = 0; dt < 4; ++dt) o[dt] = (f32x4){0.f, 0.f, 0.f, 0.f};
; #pragma unroll
;             for (int ii = 0; ii < 4; ++ii) {
;                 const int i = 4 * hf + ii;
; #pragma unroll
;                 for (int dt = 0; dt < 4; ++dt) { const int dh = 16 * dt + fr;
;                     const bf16x8 vf = *(const LAS bf16x8*)(VL + ((rs + i) & 7) * 8192 + dh * 128 + ((((cs >> 3) + fq) ^ att_fv(dh)) << 4));
;                     o[dt] = MFMA16(vf, pb[ii], o[dt]); }
;             }
;             LAS float* ml = (LAS float*)(lds + 131072 + 2048) + (size_t)(g * 64 + lane) * 2;
;             LAS u32x2* ol = (LAS u32x2*)(lds + 131072 + 4096) + (size_t)(g * 64 + lane) * 4;
;             if (hf == 1) {
; #pragma unroll
;                 for (int dt = 0; dt < 4; ++dt) { u32x2 w; w.x = cvt_pk_bf16(o[dt][0], o[dt][1]); w.y = cvt_pk_bf16(o[dt][2], o[dt][3]); ol[dt] = w; }
;                 ml[0] = mx; ml[1] = l;
;             }
	v_add_u32_e32 v32, s31, v49
	s_add_i32 s31, s30, 0x2000
	s_and_b32 s31, s31, 0xe000
	v_add_u32_e32 v33, s31, v49
	s_add_i32 s31, s30, 0x4000
	s_and_b32 s31, s31, 0xe000
	v_add_u32_e32 v34, s31, v49
	s_addk_i32 s30, 0x6000
	s_and_b32 s30, s30, 0xe000
	v_add_u32_e32 v35, s30, v49
	s_and_b64 vcc, exec, s[58:59]
	ds_read_b128 v[108:111], v32
	ds_read_b128 v[112:115], v32 offset:2048
	ds_read_b128 v[116:119], v32 offset:4096
	ds_read_b128 v[120:123], v32 offset:6144
	ds_read_b128 v[124:127], v33
	ds_read_b128 v[128:131], v33 offset:2048
	ds_read_b128 v[132:135], v33 offset:4096
	ds_read_b128 v[136:139], v33 offset:6144
	ds_read_b128 v[140:143], v34
	ds_read_b128 v[144:147], v34 offset:2048
	ds_read_b128 v[148:151], v34 offset:4096
	ds_read_b128 v[152:155], v34 offset:6144
	ds_read_b128 v[174:177], v35
	ds_read_b128 v[178:181], v35 offset:2048
	ds_read_b128 v[182:185], v35 offset:4096
	ds_read_b128 v[186:189], v35 offset:6144
	s_waitcnt lgkmcnt(12)
	v_mfma_f32_16x16x32_bf16 v[14:17], v[108:111], v[2:5], 0
	v_mfma_f32_16x16x32_bf16 v[24:27], v[112:115], v[2:5], 0
	v_mfma_f32_16x16x32_bf16 v[28:31], v[116:119], v[2:5], 0
	v_mfma_f32_16x16x32_bf16 v[2:5], v[120:123], v[2:5], 0
	s_waitcnt lgkmcnt(8)
	v_mfma_f32_16x16x32_bf16 v[14:17], v[124:127], v[6:9], v[14:17]
	v_mfma_f32_16x16x32_bf16 v[24:27], v[128:131], v[6:9], v[24:27]
	v_mfma_f32_16x16x32_bf16 v[28:31], v[132:135], v[6:9], v[28:31]
	v_mfma_f32_16x16x32_bf16 v[2:5], v[136:139], v[6:9], v[2:5]
	s_waitcnt lgkmcnt(4)
	v_mfma_f32_16x16x32_bf16 v[14:17], v[140:143], v[10:13], v[14:17]
	v_mfma_f32_16x16x32_bf16 v[24:27], v[144:147], v[10:13], v[24:27]
	v_mfma_f32_16x16x32_bf16 v[28:31], v[148:151], v[10:13], v[28:31]
	v_mfma_f32_16x16x32_bf16 v[2:5], v[152:155], v[10:13], v[2:5]
	s_waitcnt lgkmcnt(0)
	v_mfma_f32_16x16x32_bf16 v[14:17], v[174:177], v[20:23], v[14:17]
	v_mfma_f32_16x16x32_bf16 v[10:13], v[178:181], v[20:23], v[24:27]
	v_mfma_f32_16x16x32_bf16 v[6:9], v[182:185], v[20:23], v[28:31]
	v_mfma_f32_16x16x32_bf16 v[2:5], v[186:189], v[20:23], v[2:5]
	s_nop 7
	v_add_u32_e32 v20, 0, v59
	v_add_u32_e32 v21, 0, v57
	v_add_u32_e32 v20, 0x21000, v20
	v_add_u32_e32 v21, 0x20800, v21
	s_cbranch_vccnz .LBB0_467
	v_cvt_pk_bf16_f32 v22, v14, v15
	v_cvt_pk_bf16_f32 v23, v16, v17
	ds_write_b64 v20, v[22:23]
	v_cvt_pk_bf16_f32 v22, v10, v11
	v_cvt_pk_bf16_f32 v23, v12, v13
	ds_write_b64 v20, v[22:23] offset:8
	v_cvt_pk_bf16_f32 v22, v6, v7
	v_cvt_pk_bf16_f32 v23, v8, v9
	ds_write_b64 v20, v[22:23] offset:16
	v_cvt_pk_bf16_f32 v22, v2, v3
	v_cvt_pk_bf16_f32 v23, v4, v5
	ds_write_b64 v20, v[22:23] offset:24
	ds_write_b64 v21, v[18:19]
